# v32 + MLA loop back-edge rotated: loop-carried rotation movs hoisted above the tile barrier, single conditional back branch
# speedup vs baseline: 1.0001x; 1.0001x over previous
.LBB0_553:
	v_cndmask_b32_e64 v202, v202, v165, s[4:5]
	v_mul_f32_e32 v146, 0xbdd53b94, v202
	v_fmamk_f32 v82, v82, 0x3dd53b94, v146
	v_fmamk_f32 v83, v83, 0x3dd53b94, v146
	v_fmamk_f32 v84, v84, 0x3dd53b94, v146
	v_fmamk_f32 v85, v85, 0x3dd53b94, v146
	v_fmamk_f32 v86, v86, 0x3dd53b94, v146
	v_fmamk_f32 v87, v87, 0x3dd53b94, v146
	v_fmamk_f32 v88, v88, 0x3dd53b94, v146
	v_fmamk_f32 v89, v89, 0x3dd53b94, v146
	v_fmamk_f32 v90, v90, 0x3dd53b94, v146
	v_fmamk_f32 v91, v91, 0x3dd53b94, v146
	v_fmamk_f32 v92, v92, 0x3dd53b94, v146
	v_fmamk_f32 v93, v93, 0x3dd53b94, v146
	v_fmamk_f32 v94, v94, 0x3dd53b94, v146
	v_fmamk_f32 v95, v95, 0x3dd53b94, v146
	v_fmamk_f32 v96, v96, 0x3dd53b94, v146
	v_fmamk_f32 v97, v97, 0x3dd53b94, v146
	s_add_u32 s88, s88, 0xf0000
	v_exp_f32_e32 v229, v82
	v_exp_f32_e32 v231, v83
	v_exp_f32_e32 v227, v84
	v_exp_f32_e32 v230, v85
	v_exp_f32_e32 v226, v86
	v_exp_f32_e32 v228, v87
	v_exp_f32_e32 v224, v88
	v_exp_f32_e32 v225, v89
	v_exp_f32_e32 v221, v90
	v_exp_f32_e32 v223, v91
	v_exp_f32_e32 v220, v92
	v_exp_f32_e32 v222, v93
	v_exp_f32_e32 v217, v94
	v_exp_f32_e32 v219, v95
	v_exp_f32_e32 v216, v96
	v_exp_f32_e32 v218, v97
	s_addc_u32 s87, s87, 0
	v_add_f32_e32 v82, v162, v163
	s_waitcnt vmcnt(0)
	s_add_u32 s20, s20, 0x80000
	v_fmac_f32_e32 v82, v201, v171
	v_add_f32_e32 v171, v232, v233
	s_addc_u32 s21, s21, 0
	s_add_i32 s19, s19, 2
	v_fmac_f32_e32 v171, v82, v164
	v_pk_fma_f32 v[164:165], v[66:67], s[34:35], v[146:147] op_sel_hi:[1,0,0]
	v_pk_fma_f32 v[162:163], v[68:69], s[34:35], v[146:147] op_sel_hi:[1,0,0]
	v_pk_fma_f32 v[156:157], v[70:71], s[34:35], v[146:147] op_sel_hi:[1,0,0]
	v_pk_fma_f32 v[154:155], v[72:73], s[34:35], v[146:147] op_sel_hi:[1,0,0]
	v_pk_fma_f32 v[152:153], v[74:75], s[34:35], v[146:147] op_sel_hi:[1,0,0]
	v_pk_fma_f32 v[150:151], v[76:77], s[34:35], v[146:147] op_sel_hi:[1,0,0]
	v_pk_fma_f32 v[148:149], v[78:79], s[34:35], v[146:147] op_sel_hi:[1,0,0]
	v_pk_fma_f32 v[146:147], v[80:81], s[34:35], v[146:147] op_sel_hi:[1,0,0]
	s_cmp_ge_u32 s19, s86
	s_mov_b32 s0, s22
	s_mov_b32 s22, s23
	v_mov_b32_e32 v201, v215
	s_waitcnt vmcnt(0)
	s_barrier
	s_cbranch_scc0 .LBB0_543
